# e31+e29+e28: role priorities, B-loop alpha test, B-loop wait-state nops filled with useful instructions (233 instr per tile)
# speedup vs baseline: 1.0042x; 1.0042x over previous
; __device__ __forceinline__ int crow(int r, int hi) { return (r & 3) + 8 * (r >> 2) + 4 * hi; }
; __device__ __forceinline__ int crow(int r, int hi) { return (r & 3) + 8 * (r >> 2) + 4 * hi; }
; #define DMA_K(j_, b_) do { const char* kb_ = (const char*)Kh + (size_t)(j_) * (64 * LD * 2); _Pragma("unroll") for (int i = 0; i < 4; ++i) \
;     __builtin_amdgcn_global_load_lds((const unsigned*)(kb_ + kgo[i]), (LAS unsigned*)(K_las + (b_) * 16384 + (4 * a + i) * 1024), 16, 0, 0); } while (0)
; #define DMA_V(j_, b_) do { const char* vb_ = (const char*)Vh + (size_t)(j_) * (64 * LD * 2); _Pragma("unroll") for (int hf = 0; hf < 2; ++hf) _Pragma("unroll") for (int i = 0; i < 4; ++i) \
;     __builtin_amdgcn_global_load_lds((const unsigned*)(vb_ + hf * 256 + vgo[i]), (LAS unsigned*)(V_las + (b_) * 32768 + hf * 16384 + (4 * a + i) * 1024), 16, 0, 0); } while (0)
; __device__ __forceinline__ void attn_unit2(const bf16* __restrict__ Qb, const bf16* __restrict__ Kh, const bf16* __restrict__ Vh, bf16* __restrict__ Ob,
;                                            int NT, int lim, int qrow0, const float* lut, char* lds, float* scr) {
;     ...
;       if (j + 1 < NT) DMA_K(j + 1, (j + 1) & 1);
;       if (j < NT) DMA_V(j, j & 1);
;       if (j >= 1) {
;         const float* al = al0 + ((j - 1) & 1) * 128;
;         if (__any(al[r32] < 1.f) || __any(al[32 + r32] < 1.f)) {
; #pragma unroll
;           for (int rb = 0; rb < 2; ++rb)
; #pragma unroll
;             for (int d = 0; d < 4; ++d)
; #pragma unroll
;               for (int r = 0; r < 16; ++r) o[rb][d][r] *= al[rb * 32 + crow(r, hi)]; }
.LBB0_433:
	s_and_b32 s14, s10, 1
	s_lshl_b32 s15, s14, 9
	s_add_i32 s15, s4, s15
	v_lshl_add_u32 v177, v172, 2, s15
	ds_read_b32 v200, v177
	ds_read_b32 v201, v177 offset:128
	s_and_b32 s23, s9, 0x8000
	s_add_i32 s23, s6, s23
	v_lshl_add_u64 v[156:157], v[138:139], 0, s[36:37]
	s_add_i32 m0, s23, 0x8000
	v_lshl_add_u64 v[158:159], v[156:157], 0, s[54:55]
	global_load_lds_dwordx4 v[158:159], off
	v_lshl_add_u64 v[158:159], v[142:143], 0, s[36:37]
	v_lshl_add_u64 v[164:165], v[158:159], 0, s[54:55]
	s_add_i32 m0, s23, 0x8400
	s_nop 0
	v_lshl_add_u64 v[156:157], v[156:157], 0, s[68:69]
	global_load_lds_dwordx4 v[164:165], off
	s_add_i32 m0, s23, 0x8800
	v_lshl_add_u64 v[164:165], v[144:145], 0, s[36:37]
	v_lshl_add_u64 v[178:179], v[164:165], 0, s[54:55]
	global_load_lds_dwordx4 v[178:179], off
	s_add_i32 m0, s23, 0x8c00
	v_lshl_add_u64 v[178:179], v[146:147], 0, s[36:37]
	v_lshl_add_u64 v[180:181], v[178:179], 0, s[54:55]
	global_load_lds_dwordx4 v[180:181], off
	v_lshl_add_u64 v[158:159], v[158:159], 0, s[68:69]
	v_lshl_add_u64 v[164:165], v[164:165], 0, s[68:69]
	v_lshl_add_u64 v[252:253], v[178:179], 0, s[68:69]
	s_waitcnt lgkmcnt(0)
	v_cmp_gt_f32_e32 vcc, 1.0, v200
	v_cmp_gt_f32_e64 s[46:47], 1.0, v201
	s_or_b64 vcc, vcc, s[46:47]
	s_cbranch_vccz .LBB0_436
.LBB0_435:
	v_add_u32_e32 v201, s15, v140
	ds_read_b128 v[178:181], v201
	ds_read_b128 v[182:185], v201 offset:32
	ds_read_b128 v[186:189], v201 offset:64
	ds_read_b128 v[190:193], v201 offset:96
	s_waitcnt lgkmcnt(0)
	v_pk_mul_f32 v[118:119], v[118:119], v[180:181]
	v_pk_mul_f32 v[120:121], v[120:121], v[182:183]
	v_pk_mul_f32 v[124:125], v[124:125], v[186:187]
	v_pk_mul_f32 v[128:129], v[128:129], v[190:191]
	v_pk_mul_f32 v[130:131], v[130:131], v[192:193]
	v_pk_mul_f32 v[126:127], v[126:127], v[188:189]
	v_pk_mul_f32 v[122:123], v[122:123], v[184:185]
	v_pk_mul_f32 v[116:117], v[116:117], v[178:179]
	v_pk_mul_f32 v[112:113], v[112:113], v[190:191]
	v_pk_mul_f32 v[108:109], v[108:109], v[186:187]
	v_pk_mul_f32 v[104:105], v[104:105], v[182:183]
	v_pk_mul_f32 v[114:115], v[114:115], v[192:193]
	v_pk_mul_f32 v[110:111], v[110:111], v[188:189]
	v_pk_mul_f32 v[106:107], v[106:107], v[184:185]
	v_pk_mul_f32 v[102:103], v[102:103], v[180:181]
	v_pk_mul_f32 v[100:101], v[100:101], v[178:179]
	v_pk_mul_f32 v[96:97], v[96:97], v[190:191]
	v_pk_mul_f32 v[92:93], v[92:93], v[186:187]
	v_pk_mul_f32 v[88:89], v[88:89], v[182:183]
	v_pk_mul_f32 v[98:99], v[98:99], v[192:193]
	v_pk_mul_f32 v[94:95], v[94:95], v[188:189]
	v_pk_mul_f32 v[90:91], v[90:91], v[184:185]
	v_pk_mul_f32 v[86:87], v[86:87], v[180:181]
	v_pk_mul_f32 v[84:85], v[84:85], v[178:179]
	v_pk_mul_f32 v[80:81], v[80:81], v[190:191]
	v_pk_mul_f32 v[76:77], v[76:77], v[186:187]
	v_pk_mul_f32 v[72:73], v[72:73], v[182:183]
	v_pk_mul_f32 v[82:83], v[82:83], v[192:193]
	v_pk_mul_f32 v[78:79], v[78:79], v[188:189]
	v_pk_mul_f32 v[74:75], v[74:75], v[184:185]
	v_pk_mul_f32 v[70:71], v[70:71], v[180:181]
	v_pk_mul_f32 v[68:69], v[68:69], v[178:179]
	ds_read_b128 v[178:181], v201 offset:128
	ds_read_b128 v[182:185], v201 offset:160
	ds_read_b128 v[186:189], v201 offset:192
	ds_read_b128 v[190:193], v201 offset:224
	s_waitcnt lgkmcnt(0)
	v_pk_mul_f32 v[54:55], v[54:55], v[180:181]
	v_pk_mul_f32 v[56:57], v[56:57], v[182:183]
	v_pk_mul_f32 v[60:61], v[60:61], v[186:187]
	v_pk_mul_f32 v[64:65], v[64:65], v[190:191]
	v_pk_mul_f32 v[66:67], v[66:67], v[192:193]
	v_pk_mul_f32 v[62:63], v[62:63], v[188:189]
	s_nop 0
	v_pk_mul_f32 v[58:59], v[58:59], v[184:185]
	v_pk_mul_f32 v[52:53], v[52:53], v[178:179]
	v_pk_mul_f32 v[48:49], v[48:49], v[190:191]
	v_pk_mul_f32 v[44:45], v[44:45], v[186:187]
	v_pk_mul_f32 v[40:41], v[40:41], v[182:183]
	v_pk_mul_f32 v[50:51], v[50:51], v[192:193]
	v_pk_mul_f32 v[46:47], v[46:47], v[188:189]
	v_pk_mul_f32 v[42:43], v[42:43], v[184:185]
	v_pk_mul_f32 v[38:39], v[38:39], v[180:181]
	v_pk_mul_f32 v[36:37], v[36:37], v[178:179]
	v_pk_mul_f32 v[32:33], v[32:33], v[190:191]
	v_pk_mul_f32 v[28:29], v[28:29], v[186:187]
	v_pk_mul_f32 v[24:25], v[24:25], v[182:183]
	v_pk_mul_f32 v[34:35], v[34:35], v[192:193]
	v_pk_mul_f32 v[30:31], v[30:31], v[188:189]
	v_pk_mul_f32 v[26:27], v[26:27], v[184:185]
	v_pk_mul_f32 v[22:23], v[22:23], v[180:181]
	v_pk_mul_f32 v[20:21], v[20:21], v[178:179]
	v_pk_mul_f32 v[16:17], v[16:17], v[190:191]
	v_pk_mul_f32 v[12:13], v[12:13], v[186:187]
	v_pk_mul_f32 v[8:9], v[8:9], v[182:183]
	v_pk_mul_f32 v[18:19], v[18:19], v[192:193]
	v_pk_mul_f32 v[14:15], v[14:15], v[188:189]
	v_pk_mul_f32 v[10:11], v[10:11], v[184:185]
	v_pk_mul_f32 v[6:7], v[6:7], v[180:181]
	v_pk_mul_f32 v[4:5], v[4:5], v[178:179]
; #define SBAR() __builtin_amdgcn_sched_barrier(0)
; #define VRD(D0, L) const s16x4 L##0 = tr_read<v_rd_off(D0, 0, 0)>(vb), L##1 = tr_read<v_rd_off(D0, 0, 1)>(vb), L##2 = tr_read<v_rd_off(D0, 1, 0)>(vb), L##3 = tr_read<v_rd_off(D0, 1, 1)>(vb), \
;                          L##4 = tr_read<v_rd_off(D0, 2, 0)>(vb), L##5 = tr_read<v_rd_off(D0, 2, 1)>(vb), L##6 = tr_read<v_rd_off(D0, 3, 0)>(vb), L##7 = tr_read<v_rd_off(D0, 3, 1)>(vb)
; __device__ __forceinline__ void pv_four(f32x16 (&o)[2][4], int vb, bf16x8 pa0, bf16x8 pa1, bf16x8 pa2, bf16x8 pa3, bf16x8 pb0, bf16x8 pb1, bf16x8 pb2, bf16x8 pb3) {
;     ...
;   VRD(0, x); SBAR();
;   VRD(1, y); asm volatile("s_waitcnt lgkmcnt(8)" ::: "memory"); SBAR(); MMA(0, x); SBAR();
;   VRD(2, z); asm volatile("s_waitcnt lgkmcnt(8)" ::: "memory"); SBAR(); MMA(1, y); SBAR();
;   VRD(3, w); asm volatile("s_waitcnt lgkmcnt(8)" ::: "memory"); SBAR(); MMA(2, z); SBAR();
;   asm volatile("s_waitcnt lgkmcnt(0)" ::: "memory"); SBAR(); MMA(3, w);
; __device__ __forceinline__ void attn_unit2(const bf16* __restrict__ Qb, const bf16* __restrict__ Kh, const bf16* __restrict__ Vh, bf16* __restrict__ Ob,
;                                            int NT, int lim, int qrow0, const float* lut, char* lds, float* scr) {
;     ...
;         const char* ps = P0 + ((j - 1) & 1) * 16384 + lane * 16;
;         const bf16x8 pa0 = *(const bf16x8*)(ps), pa1 = *(const bf16x8*)(ps + 1024), pa2 = *(const bf16x8*)(ps + 2048), pa3 = *(const bf16x8*)(ps + 3072);
;         const bf16x8 pb0 = *(const bf16x8*)(ps + 4096), pb1 = *(const bf16x8*)(ps + 4096 + 1024), pb2 = *(const bf16x8*)(ps + 4096 + 2048), pb3 = *(const bf16x8*)(ps + 4096 + 3072);
;         const int vb = vrb + ((j - 1) & 1) * 32768 + ch * 16384;
;         pv_four(o, vb, pa0, pa1, pa2, pa3, pb0, pb1, pb2, pb3);
;       }
;       asm volatile("s_waitcnt vmcnt(0)" ::: "memory");
;       __syncthreads();
.LBB0_436:
	v_lshl_add_u32 v201, s14, 14, v175
	ds_read_b128 v[178:181], v201
	ds_read_b128 v[182:185], v201 offset:1024
	ds_read_b128 v[186:189], v201 offset:2048
	ds_read_b128 v[190:193], v201 offset:3072
	ds_read_b128 v[194:197], v201 offset:4096
	ds_read_b128 v[208:211], v201 offset:5120
	ds_read_b128 v[212:215], v201 offset:6144
	ds_read_b128 v[216:219], v201 offset:7168
	v_lshl_add_u32 v207, s14, 15, v176
	ds_read_b64_tr_b16 v[220:221], v207 offset:0
	ds_read_b64_tr_b16 v[222:223], v207 offset:0x800
	ds_read_b64_tr_b16 v[224:225], v207 offset:0x1000
	ds_read_b64_tr_b16 v[226:227], v207 offset:0x1800
	ds_read_b64_tr_b16 v[228:229], v207 offset:0x2000
	ds_read_b64_tr_b16 v[230:231], v207 offset:0x2800
	ds_read_b64_tr_b16 v[232:233], v207 offset:0x3000
	ds_read_b64_tr_b16 v[234:235], v207 offset:0x3800
	ds_read_b64_tr_b16 v[236:237], v207 offset:0x200
	ds_read_b64_tr_b16 v[238:239], v207 offset:0xa00
	ds_read_b64_tr_b16 v[240:241], v207 offset:0x1200
	ds_read_b64_tr_b16 v[242:243], v207 offset:0x1a00
	ds_read_b64_tr_b16 v[244:245], v207 offset:0x2200
	s_add_i32 m0, s23, 0xc000
	ds_read_b64_tr_b16 v[246:247], v207 offset:0x2a00
	global_load_lds_dwordx4 v[156:157], off
	s_add_i32 m0, s23, 0xc400
	ds_read_b64_tr_b16 v[248:249], v207 offset:0x3200
	global_load_lds_dwordx4 v[158:159], off
	s_add_i32 m0, s23, 0xc800
	ds_read_b64_tr_b16 v[250:251], v207 offset:0x3a00
	global_load_lds_dwordx4 v[164:165], off
	s_add_i32 m0, s23, 0xcc00
	s_nop 0
	global_load_lds_dwordx4 v[252:253], off
	s_waitcnt lgkmcnt(8)
	s_waitcnt lgkmcnt(0)
	v_mfma_f32_32x32x16_bf16 v[116:131], v[178:181], v[220:223], v[116:131]
	v_mfma_f32_32x32x16_bf16 v[52:67], v[194:197], v[220:223], v[52:67]
	s_nop 0
	v_mfma_f32_32x32x16_bf16 v[116:131], v[182:185], v[224:227], v[116:131]
	v_mfma_f32_32x32x16_bf16 v[52:67], v[208:211], v[224:227], v[52:67]
	v_mfma_f32_32x32x16_bf16 v[116:131], v[186:189], v[228:231], v[116:131]
	v_mfma_f32_32x32x16_bf16 v[52:67], v[212:215], v[228:231], v[52:67]
	v_mfma_f32_32x32x16_bf16 v[116:131], v[190:193], v[232:235], v[116:131]
	v_mfma_f32_32x32x16_bf16 v[52:67], v[216:219], v[232:235], v[52:67]
	ds_read_b64_tr_b16 v[220:221], v207 offset:0x400
	ds_read_b64_tr_b16 v[222:223], v207 offset:0xc00
	ds_read_b64_tr_b16 v[224:225], v207 offset:0x1400
	ds_read_b64_tr_b16 v[226:227], v207 offset:0x1c00
	ds_read_b64_tr_b16 v[228:229], v207 offset:0x2400
	ds_read_b64_tr_b16 v[230:231], v207 offset:0x2c00
	ds_read_b64_tr_b16 v[232:233], v207 offset:0x3400
	ds_read_b64_tr_b16 v[234:235], v207 offset:0x3c00
	s_waitcnt lgkmcnt(8)
	v_mfma_f32_32x32x16_bf16 v[100:115], v[178:181], v[236:239], v[100:115]
	s_nop 0
	v_mfma_f32_32x32x16_bf16 v[36:51], v[194:197], v[236:239], v[36:51]
	v_mfma_f32_32x32x16_bf16 v[100:115], v[182:185], v[240:243], v[100:115]
	v_mfma_f32_32x32x16_bf16 v[36:51], v[208:211], v[240:243], v[36:51]
	v_mfma_f32_32x32x16_bf16 v[100:115], v[186:189], v[244:247], v[100:115]
	v_mfma_f32_32x32x16_bf16 v[36:51], v[212:215], v[244:247], v[36:51]
	v_mfma_f32_32x32x16_bf16 v[100:115], v[190:193], v[248:251], v[100:115]
	v_mfma_f32_32x32x16_bf16 v[36:51], v[216:219], v[248:251], v[36:51]
	ds_read_b64_tr_b16 v[236:237], v207 offset:0x600
	ds_read_b64_tr_b16 v[238:239], v207 offset:0xe00
	ds_read_b64_tr_b16 v[240:241], v207 offset:0x1600
	ds_read_b64_tr_b16 v[242:243], v207 offset:0x1e00
	ds_read_b64_tr_b16 v[244:245], v207 offset:0x2600
	ds_read_b64_tr_b16 v[246:247], v207 offset:0x2e00
	ds_read_b64_tr_b16 v[248:249], v207 offset:0x3600
	ds_read_b64_tr_b16 v[250:251], v207 offset:0x3e00
	s_waitcnt lgkmcnt(8)
	s_nop 0
	v_mfma_f32_32x32x16_bf16 v[84:99], v[178:181], v[220:223], v[84:99]
	v_mfma_f32_32x32x16_bf16 v[20:35], v[194:197], v[220:223], v[20:35]
	v_mfma_f32_32x32x16_bf16 v[84:99], v[182:185], v[224:227], v[84:99]
	v_mfma_f32_32x32x16_bf16 v[20:35], v[208:211], v[224:227], v[20:35]
	v_mfma_f32_32x32x16_bf16 v[84:99], v[186:189], v[228:231], v[84:99]
	v_mfma_f32_32x32x16_bf16 v[20:35], v[212:215], v[228:231], v[20:35]
	v_mfma_f32_32x32x16_bf16 v[84:99], v[190:193], v[232:235], v[84:99]
	v_mfma_f32_32x32x16_bf16 v[20:35], v[216:219], v[232:235], v[20:35]
	s_waitcnt lgkmcnt(0)
	v_mfma_f32_32x32x16_bf16 v[68:83], v[178:181], v[236:239], v[68:83]
	s_add_i32 s9, s9, 0x8000
	s_waitcnt vmcnt(0)
	s_add_u32 s36, s36, 0x40000
	s_addc_u32 s37, s37, 0
	s_add_i32 s14, s10, 1
	s_addk_i32 s7, 0x4000
	s_cmp_eq_u32 s8, s36
	v_mfma_f32_32x32x16_bf16 v[4:19], v[194:197], v[236:239], v[4:19]
	s_waitcnt vmcnt(0)
	s_barrier
	v_mfma_f32_32x32x16_bf16 v[68:83], v[182:185], v[240:243], v[68:83]
	v_mfma_f32_32x32x16_bf16 v[4:19], v[208:211], v[240:243], v[4:19]
	v_mfma_f32_32x32x16_bf16 v[68:83], v[186:189], v[244:247], v[68:83]
	v_mfma_f32_32x32x16_bf16 v[4:19], v[212:215], v[244:247], v[4:19]
	v_mfma_f32_32x32x16_bf16 v[68:83], v[190:193], v[248:251], v[68:83]
	v_mfma_f32_32x32x16_bf16 v[4:19], v[216:219], v[248:251], v[4:19]
	s_cbranch_scc1 .LBB0_439
	s_mov_b32 s10, s14
	s_cmp_lt_u32 s10, s5
	s_cselect_b64 s[38:39], -1, 0
	s_cmp_ge_u32 s10, s5
	s_cbranch_scc0 .LBB0_432
	s_branch .LBB0_433
	s_nop 0
